# heavy workgroups: group_wait release barrier merged into the barrier that closes the w_out transposes (they read no acquired data), plus the early arrival-counter read so wave 0 is not delayed by its
# baseline (speedup 1.0000x reference)
; #define LAS __attribute__((address_space(3)))
; template <bool PERMUTE>
; __device__ __forceinline__ void p0_transpose_item(const float* W, int K, int N, bf16* WT, LAS float* scr, int item, int lane) {
;     const int nblk = N / 32, kb = item / nblk, nb = item % nblk, k0 = 64 * kb, n0 = 32 * nb;
;     float wv[32];
; #pragma unroll
;     for (int i = 0; i < 32; ++i) wv[i] = __builtin_nontemporal_load(W + (size_t)(k0 + 2 * i + (lane >> 5)) * N + n0 + (lane & 31));
; #pragma unroll
;     for (int i = 0; i < 32; ++i) scr[(2 * i + (lane >> 5)) * 33 + (lane & 31)] = wv[i];
; __global__ void __launch_bounds__(NWAVES * 64, 2) fwd_megakernel(Args a) {
;     ...
;                 {
;                     LAS float* scr = (LAS float*)(lds + wave * 16384);
;                     constexpr int I_OUT = (DMIX / 64) * (DM / 32);
;                     const int it = ((blockIdx.x & 7) * 24 + (l - 8)) * NWAVES + wave;
;                     if (it < I_OUT) p0_transpose_item<false>(a.w_out, DMIX, DM, WOUT, scr, it, lane);
;                     __syncthreads();
.LBB0_274:
	s_or_b64 exec, exec, s[0:1]
	v_and_b32_e32 v134, 31, v230
	v_lshrrev_b32_e32 v0, 5, v231
	v_lshrrev_b32_e32 v127, 3, v231
	v_lshlrev_b32_e32 v1, 3, v230
	v_and_b32_e32 v130, 56, v1
	v_mov_b32_e32 v131, 0
	v_mul_u32_u24_e32 v123, 0x90, v127
	v_mul_u32_u24_e32 v125, 0x90, v134
	v_lshlrev_b32_e32 v129, 3, v0
	v_lshlrev_b32_e32 v135, 2, v0
	s_and_b32 s33, s98, 7
	s_lshr_b32 s90, s98, 3
	v_lshrrev_b32_e32 v136, 5, v231
	v_lshlrev_b32_e32 v98, 1, v130
	v_readlane_b32 s1, v253, 29
	s_lshl_b32 s0, s98, 4
	s_nop 2
	s_lshl_b32 s1, s1, 1
	s_add_i32 s0, s0, s1
	s_ashr_i32 s1, s0, 31
	s_lshr_b32 s1, s1, 27
	s_add_i32 s1, s0, s1
	s_and_b32 s2, s1, 0x7ffffe0
	s_sub_i32 s0, s0, s2
	s_lshl_b32 s1, s1, 1
	s_lshl_b32 s0, s0, 5
	s_and_b32 s2, s1, 0xffffffc0
	s_ashr_i32 s1, s0, 31
	v_readlane_b32 s12, v253, 4
	v_or_b32_e32 v2, s2, v136
	s_lshl_b64 s[4:5], s[0:1], 2
	v_readlane_b32 s26, v253, 18
	v_readlane_b32 s27, v253, 19
	s_add_u32 s4, s26, s4
	v_or_b32_e32 v8, 2, v2
	v_or_b32_e32 v10, 4, v2
	v_or_b32_e32 v12, 6, v2
	v_or_b32_e32 v14, 8, v2
	v_or_b32_e32 v16, 10, v2
	v_or_b32_e32 v18, 12, v2
	v_or_b32_e32 v20, 14, v2
	s_addc_u32 s5, s27, s5
	v_lshlrev_b32_e32 v0, 2, v134
	v_mov_b32_e32 v1, 0
	v_ashrrev_i32_e32 v3, 31, v2
	v_ashrrev_i32_e32 v9, 31, v8
	v_ashrrev_i32_e32 v11, 31, v10
	v_ashrrev_i32_e32 v13, 31, v12
	v_ashrrev_i32_e32 v15, 31, v14
	v_ashrrev_i32_e32 v17, 31, v16
	v_ashrrev_i32_e32 v19, 31, v18
	v_ashrrev_i32_e32 v21, 31, v20
	v_lshl_add_u64 v[4:5], s[4:5], 0, v[0:1]
	v_lshlrev_b64 v[6:7], 12, v[2:3]
	v_lshlrev_b64 v[8:9], 12, v[8:9]
	v_lshlrev_b64 v[10:11], 12, v[10:11]
	v_lshlrev_b64 v[12:13], 12, v[12:13]
	v_lshlrev_b64 v[14:15], 12, v[14:15]
	v_lshlrev_b64 v[16:17], 12, v[16:17]
	v_lshlrev_b64 v[18:19], 12, v[18:19]
	v_lshlrev_b64 v[20:21], 12, v[20:21]
	v_lshl_add_u64 v[6:7], v[4:5], 0, v[6:7]
	v_lshl_add_u64 v[8:9], v[4:5], 0, v[8:9]
	v_lshl_add_u64 v[10:11], v[4:5], 0, v[10:11]
	v_lshl_add_u64 v[12:13], v[4:5], 0, v[12:13]
	v_lshl_add_u64 v[14:15], v[4:5], 0, v[14:15]
	v_lshl_add_u64 v[16:17], v[4:5], 0, v[16:17]
	v_lshl_add_u64 v[18:19], v[4:5], 0, v[18:19]
	v_lshl_add_u64 v[20:21], v[4:5], 0, v[20:21]
	global_load_dword v22, v[6:7], off nt
	global_load_dword v23, v[8:9], off nt
	global_load_dword v24, v[10:11], off nt
	global_load_dword v25, v[12:13], off nt
	global_load_dword v26, v[14:15], off nt
	global_load_dword v27, v[16:17], off nt
	global_load_dword v28, v[18:19], off nt
	global_load_dword v29, v[20:21], off nt
	v_or_b32_e32 v6, 16, v2
	v_or_b32_e32 v8, 18, v2
	v_or_b32_e32 v10, 20, v2
	v_or_b32_e32 v12, 22, v2
	v_or_b32_e32 v14, 24, v2
	v_or_b32_e32 v16, 26, v2
	v_or_b32_e32 v18, 28, v2
	v_or_b32_e32 v20, 30, v2
	v_ashrrev_i32_e32 v7, 31, v6
	v_ashrrev_i32_e32 v9, 31, v8
	v_ashrrev_i32_e32 v11, 31, v10
	v_ashrrev_i32_e32 v13, 31, v12
	v_ashrrev_i32_e32 v15, 31, v14
	v_ashrrev_i32_e32 v17, 31, v16
	v_ashrrev_i32_e32 v19, 31, v18
	v_ashrrev_i32_e32 v21, 31, v20
	v_lshlrev_b64 v[6:7], 12, v[6:7]
	v_lshlrev_b64 v[8:9], 12, v[8:9]
	v_lshlrev_b64 v[10:11], 12, v[10:11]
	v_lshlrev_b64 v[12:13], 12, v[12:13]
	v_lshlrev_b64 v[14:15], 12, v[14:15]
	v_lshlrev_b64 v[16:17], 12, v[16:17]
	v_lshlrev_b64 v[18:19], 12, v[18:19]
	v_lshlrev_b64 v[20:21], 12, v[20:21]
	v_lshl_add_u64 v[6:7], v[4:5], 0, v[6:7]
	v_lshl_add_u64 v[8:9], v[4:5], 0, v[8:9]
	v_lshl_add_u64 v[10:11], v[4:5], 0, v[10:11]
	v_lshl_add_u64 v[12:13], v[4:5], 0, v[12:13]
	v_lshl_add_u64 v[14:15], v[4:5], 0, v[14:15]
	v_lshl_add_u64 v[16:17], v[4:5], 0, v[16:17]
	v_lshl_add_u64 v[18:19], v[4:5], 0, v[18:19]
	v_lshl_add_u64 v[20:21], v[4:5], 0, v[20:21]
	global_load_dword v30, v[6:7], off nt
	global_load_dword v31, v[8:9], off nt
	global_load_dword v32, v[10:11], off nt
	global_load_dword v33, v[12:13], off nt
	global_load_dword v34, v[14:15], off nt
	global_load_dword v35, v[16:17], off nt
	global_load_dword v36, v[18:19], off nt
	global_load_dword v37, v[20:21], off nt
	v_or_b32_e32 v6, 32, v2
	v_or_b32_e32 v8, 34, v2
	v_or_b32_e32 v10, 36, v2
	v_or_b32_e32 v12, 38, v2
	v_or_b32_e32 v14, 40, v2
	v_or_b32_e32 v16, 42, v2
	v_or_b32_e32 v18, 44, v2
	v_or_b32_e32 v20, 46, v2
	v_ashrrev_i32_e32 v7, 31, v6
	v_ashrrev_i32_e32 v9, 31, v8
	v_ashrrev_i32_e32 v11, 31, v10
	v_ashrrev_i32_e32 v13, 31, v12
	v_ashrrev_i32_e32 v15, 31, v14
	v_ashrrev_i32_e32 v17, 31, v16
	v_ashrrev_i32_e32 v19, 31, v18
	v_ashrrev_i32_e32 v21, 31, v20
	v_lshlrev_b64 v[6:7], 12, v[6:7]
	v_lshlrev_b64 v[8:9], 12, v[8:9]
	v_lshlrev_b64 v[10:11], 12, v[10:11]
	v_lshlrev_b64 v[12:13], 12, v[12:13]
	v_lshlrev_b64 v[14:15], 12, v[14:15]
	v_lshlrev_b64 v[16:17], 12, v[16:17]
	v_lshlrev_b64 v[18:19], 12, v[18:19]
	v_lshlrev_b64 v[20:21], 12, v[20:21]
	v_lshl_add_u64 v[6:7], v[4:5], 0, v[6:7]
	v_lshl_add_u64 v[8:9], v[4:5], 0, v[8:9]
	v_lshl_add_u64 v[10:11], v[4:5], 0, v[10:11]
	v_lshl_add_u64 v[12:13], v[4:5], 0, v[12:13]
	v_lshl_add_u64 v[14:15], v[4:5], 0, v[14:15]
	v_lshl_add_u64 v[16:17], v[4:5], 0, v[16:17]
	v_lshl_add_u64 v[18:19], v[4:5], 0, v[18:19]
	v_lshl_add_u64 v[20:21], v[4:5], 0, v[20:21]
	global_load_dword v38, v[6:7], off nt
	global_load_dword v39, v[8:9], off nt
	global_load_dword v40, v[10:11], off nt
	global_load_dword v41, v[12:13], off nt
	global_load_dword v42, v[14:15], off nt
	global_load_dword v43, v[16:17], off nt
	global_load_dword v44, v[18:19], off nt
	s_nop 0
	global_load_dword v20, v[20:21], off nt
	v_or_b32_e32 v6, 48, v2
	v_or_b32_e32 v8, 50, v2
	v_or_b32_e32 v10, 52, v2
	v_or_b32_e32 v12, 54, v2
	v_or_b32_e32 v14, 56, v2
	v_or_b32_e32 v16, 58, v2
	v_or_b32_e32 v18, 60, v2
	v_or_b32_e32 v2, 62, v2
	v_ashrrev_i32_e32 v7, 31, v6
	v_ashrrev_i32_e32 v9, 31, v8
; #define LAS __attribute__((address_space(3)))
; template <bool PERMUTE>
; __device__ __forceinline__ void p0_transpose_item(const float* W, int K, int N, bf16* WT, LAS float* scr, int item, int lane) {
;     const int nblk = N / 32, kb = item / nblk, nb = item % nblk, k0 = 64 * kb, n0 = 32 * nb;
;     float wv[32];
; #pragma unroll
;     for (int i = 0; i < 32; ++i) wv[i] = __builtin_nontemporal_load(W + (size_t)(k0 + 2 * i + (lane >> 5)) * N + n0 + (lane & 31));
; #pragma unroll
;     for (int i = 0; i < 32; ++i) scr[(2 * i + (lane >> 5)) * 33 + (lane & 31)] = wv[i];
; __global__ void __launch_bounds__(NWAVES * 64, 2) fwd_megakernel(Args a) {
;     ...
;                     if (it < I_OUT) p0_transpose_item<false>(a.w_out, DMIX, DM, WOUT, scr, it, lane);
	v_ashrrev_i32_e32 v11, 31, v10
	v_ashrrev_i32_e32 v3, 31, v2
	v_lshlrev_b64 v[6:7], 12, v[6:7]
	v_lshlrev_b64 v[8:9], 12, v[8:9]
	v_lshlrev_b64 v[10:11], 12, v[10:11]
	v_ashrrev_i32_e32 v13, 31, v12
	v_ashrrev_i32_e32 v15, 31, v14
	v_ashrrev_i32_e32 v17, 31, v16
	v_ashrrev_i32_e32 v19, 31, v18
	v_lshlrev_b64 v[2:3], 12, v[2:3]
	v_lshl_add_u64 v[6:7], v[4:5], 0, v[6:7]
	v_lshl_add_u64 v[8:9], v[4:5], 0, v[8:9]
	v_lshl_add_u64 v[10:11], v[4:5], 0, v[10:11]
	v_lshlrev_b64 v[12:13], 12, v[12:13]
	v_lshlrev_b64 v[14:15], 12, v[14:15]
	v_lshlrev_b64 v[16:17], 12, v[16:17]
	v_lshlrev_b64 v[18:19], 12, v[18:19]
	v_lshl_add_u64 v[2:3], v[4:5], 0, v[2:3]
	v_lshl_add_u64 v[12:13], v[4:5], 0, v[12:13]
	v_lshl_add_u64 v[14:15], v[4:5], 0, v[14:15]
	v_lshl_add_u64 v[16:17], v[4:5], 0, v[16:17]
	v_lshl_add_u64 v[18:19], v[4:5], 0, v[18:19]
	global_load_dword v4, v[6:7], off nt
	global_load_dword v5, v[8:9], off nt
	s_nop 0
	global_load_dword v6, v[10:11], off nt
	global_load_dword v7, v[12:13], off nt
	global_load_dword v8, v[14:15], off nt
	global_load_dword v9, v[16:17], off nt
	s_nop 0
	global_load_dword v10, v[18:19], off nt
	s_nop 0
	global_load_dword v2, v[2:3], off nt
	v_readlane_b32 s11, v253, 29
	s_lshl_b32 s10, s98, 4
	s_nop 2
	s_lshl_b32 s11, s11, 1
	s_add_i32 s10, s10, s11
	s_add_i32 s10, s10, 1
	s_ashr_i32 s11, s10, 31
	s_lshr_b32 s11, s11, 27
	s_add_i32 s11, s10, s11
	s_and_b32 s6, s11, 0x7ffffe0
	s_sub_i32 s10, s10, s6
	s_lshl_b32 s11, s11, 1
	s_lshl_b32 s10, s10, 5
	s_and_b32 s6, s11, 0xffffffc0
	s_ashr_i32 s11, s10, 31
	v_readlane_b32 s12, v253, 4
	v_or_b32_e32 v174, s6, v136
	s_lshl_b64 vcc, s[10:11], 2
	v_readlane_b32 s26, v253, 18
	v_readlane_b32 s27, v253, 19
	s_add_u32 vcc_lo, s26, vcc_lo
	v_or_b32_e32 v180, 2, v174
	v_or_b32_e32 v182, 4, v174
	v_or_b32_e32 v184, 6, v174
	v_or_b32_e32 v186, 8, v174
	v_or_b32_e32 v188, 10, v174
	v_or_b32_e32 v190, 12, v174
	v_or_b32_e32 v192, 14, v174
	s_addc_u32 vcc_hi, s27, vcc_hi
	v_lshlrev_b32_e32 v172, 2, v134
	v_mov_b32_e32 v173, 0
	v_ashrrev_i32_e32 v175, 31, v174
	v_ashrrev_i32_e32 v181, 31, v180
	v_ashrrev_i32_e32 v183, 31, v182
	v_ashrrev_i32_e32 v185, 31, v184
	v_ashrrev_i32_e32 v187, 31, v186
	v_ashrrev_i32_e32 v189, 31, v188
	v_ashrrev_i32_e32 v191, 31, v190
	v_ashrrev_i32_e32 v193, 31, v192
	v_lshl_add_u64 v[176:177], vcc, 0, v[172:173]
	v_lshlrev_b64 v[178:179], 12, v[174:175]
	v_lshlrev_b64 v[180:181], 12, v[180:181]
	v_lshlrev_b64 v[182:183], 12, v[182:183]
	v_lshlrev_b64 v[184:185], 12, v[184:185]
	v_lshlrev_b64 v[186:187], 12, v[186:187]
	v_lshlrev_b64 v[188:189], 12, v[188:189]
	v_lshlrev_b64 v[190:191], 12, v[190:191]
	v_lshlrev_b64 v[192:193], 12, v[192:193]
	v_lshl_add_u64 v[178:179], v[176:177], 0, v[178:179]
	v_lshl_add_u64 v[180:181], v[176:177], 0, v[180:181]
	v_lshl_add_u64 v[182:183], v[176:177], 0, v[182:183]
	v_lshl_add_u64 v[184:185], v[176:177], 0, v[184:185]
	v_lshl_add_u64 v[186:187], v[176:177], 0, v[186:187]
	v_lshl_add_u64 v[188:189], v[176:177], 0, v[188:189]
	v_lshl_add_u64 v[190:191], v[176:177], 0, v[190:191]
	v_lshl_add_u64 v[192:193], v[176:177], 0, v[192:193]
	global_load_dword v194, v[178:179], off nt
	global_load_dword v195, v[180:181], off nt
	global_load_dword v196, v[182:183], off nt
	global_load_dword v197, v[184:185], off nt
	global_load_dword v198, v[186:187], off nt
	global_load_dword v199, v[188:189], off nt
	global_load_dword v200, v[190:191], off nt
	global_load_dword v201, v[192:193], off nt
	v_or_b32_e32 v178, 16, v174
	v_or_b32_e32 v180, 18, v174
	v_or_b32_e32 v182, 20, v174
	v_or_b32_e32 v184, 22, v174
	v_or_b32_e32 v186, 24, v174
	v_or_b32_e32 v188, 26, v174
	v_or_b32_e32 v190, 28, v174
	v_or_b32_e32 v192, 30, v174
	v_ashrrev_i32_e32 v179, 31, v178
	v_ashrrev_i32_e32 v181, 31, v180
	v_ashrrev_i32_e32 v183, 31, v182
	v_ashrrev_i32_e32 v185, 31, v184
	v_ashrrev_i32_e32 v187, 31, v186
	v_ashrrev_i32_e32 v189, 31, v188
	v_ashrrev_i32_e32 v191, 31, v190
	v_ashrrev_i32_e32 v193, 31, v192
	v_lshlrev_b64 v[178:179], 12, v[178:179]
	v_lshlrev_b64 v[180:181], 12, v[180:181]
	v_lshlrev_b64 v[182:183], 12, v[182:183]
	v_lshlrev_b64 v[184:185], 12, v[184:185]
	v_lshlrev_b64 v[186:187], 12, v[186:187]
	v_lshlrev_b64 v[188:189], 12, v[188:189]
	v_lshlrev_b64 v[190:191], 12, v[190:191]
	v_lshlrev_b64 v[192:193], 12, v[192:193]
	v_lshl_add_u64 v[178:179], v[176:177], 0, v[178:179]
	v_lshl_add_u64 v[180:181], v[176:177], 0, v[180:181]
	v_lshl_add_u64 v[182:183], v[176:177], 0, v[182:183]
	v_lshl_add_u64 v[184:185], v[176:177], 0, v[184:185]
	v_lshl_add_u64 v[186:187], v[176:177], 0, v[186:187]
	v_lshl_add_u64 v[188:189], v[176:177], 0, v[188:189]
	v_lshl_add_u64 v[190:191], v[176:177], 0, v[190:191]
	v_lshl_add_u64 v[192:193], v[176:177], 0, v[192:193]
	global_load_dword v202, v[178:179], off nt
	global_load_dword v203, v[180:181], off nt
	global_load_dword v204, v[182:183], off nt
	global_load_dword v205, v[184:185], off nt
	global_load_dword v206, v[186:187], off nt
	global_load_dword v207, v[188:189], off nt
	global_load_dword v208, v[190:191], off nt
	global_load_dword v209, v[192:193], off nt
	v_or_b32_e32 v178, 32, v174
	v_or_b32_e32 v180, 34, v174
	v_or_b32_e32 v182, 36, v174
	v_or_b32_e32 v184, 38, v174
	v_or_b32_e32 v186, 40, v174
	v_or_b32_e32 v188, 42, v174
	v_or_b32_e32 v190, 44, v174
	v_or_b32_e32 v192, 46, v174
	v_ashrrev_i32_e32 v179, 31, v178
	v_ashrrev_i32_e32 v181, 31, v180
	v_ashrrev_i32_e32 v183, 31, v182
	v_ashrrev_i32_e32 v185, 31, v184
	v_ashrrev_i32_e32 v187, 31, v186
	v_ashrrev_i32_e32 v189, 31, v188
	v_ashrrev_i32_e32 v191, 31, v190
	v_ashrrev_i32_e32 v193, 31, v192
	v_lshlrev_b64 v[178:179], 12, v[178:179]
; #define LAS __attribute__((address_space(3)))
; #define LDS_WAIT() asm volatile("s_waitcnt lgkmcnt(0)" ::: "memory")
; __device__ __forceinline__ unsigned pk2(float lo, float hi) { return pg8::cvt_pk_bf16(lo, hi); }
; template <bool PERMUTE>
; __device__ __forceinline__ void p0_transpose_item(const float* W, int K, int N, bf16* WT, LAS float* scr, int item, int lane) {
;     const int nblk = N / 32, kb = item / nblk, nb = item % nblk, k0 = 64 * kb, n0 = 32 * nb;
;     float wv[32];
; #pragma unroll
;     for (int i = 0; i < 32; ++i) wv[i] = __builtin_nontemporal_load(W + (size_t)(k0 + 2 * i + (lane >> 5)) * N + n0 + (lane & 31));
; #pragma unroll
;     for (int i = 0; i < 32; ++i) scr[(2 * i + (lane >> 5)) * 33 + (lane & 31)] = wv[i];
;     LDS_WAIT(); asm volatile("" ::: "memory");
;     const int c = lane & 7;
; #pragma unroll
;     for (int j = 0; j < 4; ++j) { const int n = (lane >> 3) + 8 * j; const LAS float* s = scr + (8 * c) * 33 + n;
;         v4u o; o.x = pk2(s[0 * 33], s[1 * 33]); o.y = pk2(s[2 * 33], s[3 * 33]); o.z = pk2(s[4 * 33], s[5 * 33]); o.w = pk2(s[6 * 33], s[7 * 33]);
;         const int dr = PERMUTE ? win_dst_row(n0 + n) : (n0 + n);
;         if (PERMUTE && n0 < 4096) __builtin_nontemporal_store(o, (v4u*)(WT + (size_t)dr * K + k0 + 8 * c));
;         else *(v4u*)(WT + (size_t)dr * K + k0 + 8 * c) = o; }
;     LDS_WAIT(); asm volatile("" ::: "memory");
; }
	v_lshlrev_b64 v[180:181], 12, v[180:181]
	v_lshlrev_b64 v[182:183], 12, v[182:183]
	v_lshlrev_b64 v[184:185], 12, v[184:185]
	v_lshlrev_b64 v[186:187], 12, v[186:187]
	v_lshlrev_b64 v[188:189], 12, v[188:189]
	v_lshlrev_b64 v[190:191], 12, v[190:191]
	v_lshlrev_b64 v[192:193], 12, v[192:193]
	v_lshl_add_u64 v[178:179], v[176:177], 0, v[178:179]
	v_lshl_add_u64 v[180:181], v[176:177], 0, v[180:181]
	v_lshl_add_u64 v[182:183], v[176:177], 0, v[182:183]
	v_lshl_add_u64 v[184:185], v[176:177], 0, v[184:185]
	v_lshl_add_u64 v[186:187], v[176:177], 0, v[186:187]
	v_lshl_add_u64 v[188:189], v[176:177], 0, v[188:189]
	v_lshl_add_u64 v[190:191], v[176:177], 0, v[190:191]
	v_lshl_add_u64 v[192:193], v[176:177], 0, v[192:193]
	global_load_dword v210, v[178:179], off nt
	global_load_dword v211, v[180:181], off nt
	global_load_dword v212, v[182:183], off nt
	global_load_dword v213, v[184:185], off nt
	global_load_dword v214, v[186:187], off nt
	global_load_dword v215, v[188:189], off nt
	global_load_dword v216, v[190:191], off nt
	s_nop 0
	global_load_dword v192, v[192:193], off nt
	v_or_b32_e32 v178, 48, v174
	v_or_b32_e32 v180, 50, v174
	v_or_b32_e32 v182, 52, v174
	v_or_b32_e32 v184, 54, v174
	v_or_b32_e32 v186, 56, v174
	v_or_b32_e32 v188, 58, v174
	v_or_b32_e32 v190, 60, v174
	v_or_b32_e32 v174, 62, v174
	v_ashrrev_i32_e32 v179, 31, v178
	v_ashrrev_i32_e32 v181, 31, v180
	v_ashrrev_i32_e32 v183, 31, v182
	v_ashrrev_i32_e32 v175, 31, v174
	v_lshlrev_b64 v[178:179], 12, v[178:179]
	v_lshlrev_b64 v[180:181], 12, v[180:181]
	v_lshlrev_b64 v[182:183], 12, v[182:183]
	v_ashrrev_i32_e32 v185, 31, v184
	v_ashrrev_i32_e32 v187, 31, v186
	v_ashrrev_i32_e32 v189, 31, v188
	v_ashrrev_i32_e32 v191, 31, v190
	v_lshlrev_b64 v[174:175], 12, v[174:175]
	v_lshl_add_u64 v[178:179], v[176:177], 0, v[178:179]
	v_lshl_add_u64 v[180:181], v[176:177], 0, v[180:181]
	v_lshl_add_u64 v[182:183], v[176:177], 0, v[182:183]
	v_lshlrev_b64 v[184:185], 12, v[184:185]
	v_lshlrev_b64 v[186:187], 12, v[186:187]
	v_lshlrev_b64 v[188:189], 12, v[188:189]
	v_lshlrev_b64 v[190:191], 12, v[190:191]
	v_lshl_add_u64 v[174:175], v[176:177], 0, v[174:175]
	v_lshl_add_u64 v[184:185], v[176:177], 0, v[184:185]
	v_lshl_add_u64 v[186:187], v[176:177], 0, v[186:187]
	v_lshl_add_u64 v[188:189], v[176:177], 0, v[188:189]
	v_lshl_add_u64 v[190:191], v[176:177], 0, v[190:191]
	global_load_dword v176, v[178:179], off nt
	global_load_dword v177, v[180:181], off nt
	s_nop 0
	global_load_dword v178, v[182:183], off nt
	global_load_dword v179, v[184:185], off nt
	global_load_dword v180, v[186:187], off nt
	global_load_dword v181, v[188:189], off nt
	s_nop 0
	global_load_dword v182, v[190:191], off nt
	s_nop 0
	global_load_dword v174, v[174:175], off nt
	v_mul_u32_u24_e32 v3, 0x84, v136
	v_readlane_b32 s1, v253, 30
	s_ashr_i32 s3, s2, 31
	s_lshl_b64 s[2:3], s[2:3], 1
	v_add3_u32 v0, s1, v0, v3
	v_add_u32_e32 v3, 0x400, v0
	s_waitcnt vmcnt(62)
	ds_write2_b32 v0, v22, v23 offset1:66
	s_waitcnt vmcnt(60)
	ds_write2_b32 v0, v24, v25 offset0:132 offset1:198
	s_waitcnt vmcnt(58)
	ds_write2_b32 v3, v26, v27 offset0:8 offset1:74
	s_waitcnt vmcnt(56)
	ds_write2_b32 v3, v28, v29 offset0:140 offset1:206
	v_add_u32_e32 v3, 0x800, v0
	s_waitcnt vmcnt(54)
	ds_write2_b32 v3, v30, v31 offset0:16 offset1:82
	s_waitcnt vmcnt(52)
	ds_write2_b32 v3, v32, v33 offset0:148 offset1:214
	v_add_u32_e32 v3, 0xc00, v0
	s_waitcnt vmcnt(50)
	ds_write2_b32 v3, v34, v35 offset0:24 offset1:90
	s_waitcnt vmcnt(48)
	ds_write2_b32 v3, v36, v37 offset0:156 offset1:222
	v_add_u32_e32 v3, 0x1000, v0
	s_waitcnt vmcnt(46)
	ds_write2_b32 v3, v38, v39 offset0:32 offset1:98
	s_waitcnt vmcnt(44)
	ds_write2_b32 v3, v40, v41 offset0:164 offset1:230
	v_add_u32_e32 v3, 0x1400, v0
	s_waitcnt vmcnt(42)
	ds_write2_b32 v3, v42, v43 offset0:40 offset1:106
	s_waitcnt vmcnt(40)
	ds_write2_b32 v3, v44, v20 offset0:172 offset1:238
	v_add_u32_e32 v3, 0x1800, v0
	v_add_u32_e32 v0, 0x1c00, v0
	s_waitcnt vmcnt(38)
	ds_write2_b32 v3, v4, v5 offset0:48 offset1:114
	s_waitcnt vmcnt(36)
	ds_write2_b32 v3, v6, v7 offset0:180 offset1:246
	s_waitcnt vmcnt(34)
	ds_write2_b32 v0, v8, v9 offset0:56 offset1:122
	s_waitcnt vmcnt(32)
	ds_write2_b32 v0, v10, v2 offset0:188 offset1:254
	s_waitcnt lgkmcnt(0)
	v_mul_u32_u24_e32 v0, 0x84, v130
	v_lshlrev_b32_e32 v2, 2, v127
	v_add3_u32 v12, s1, v0, v2
	ds_read2_b32 v[2:3], v12 offset1:33
	s_waitcnt lgkmcnt(0)
	v_cvt_pk_bf16_f32 v2, v2, v3
	ds_read2_b32 v[4:5], v12 offset0:66 offset1:99
	s_waitcnt lgkmcnt(0)
	v_cvt_pk_bf16_f32 v3, v4, v5
	ds_read2_b32 v[4:5], v12 offset0:132 offset1:165
	s_waitcnt lgkmcnt(0)
	v_cvt_pk_bf16_f32 v4, v4, v5
	ds_read2_b32 v[6:7], v12 offset0:198 offset1:231
	v_readlane_b32 s4, v253, 48
	v_readlane_b32 s5, v253, 49
	s_add_u32 s2, s4, s2
	s_waitcnt lgkmcnt(0)
	v_cvt_pk_bf16_f32 v5, v6, v7
	v_or_b32_e32 v6, s0, v127
	s_addc_u32 s3, s5, s3
	v_mov_b32_e32 v99, v1
	v_ashrrev_i32_e32 v7, 31, v6
	v_lshl_add_u64 v[8:9], s[2:3], 0, v[98:99]
	v_lshlrev_b64 v[10:11], 12, v[6:7]
	ds_read2_b32 v[0:1], v12 offset0:8 offset1:41
	v_lshl_add_u64 v[10:11], v[8:9], 0, v[10:11]
	global_store_dwordx4 v[10:11], v[2:5], off
	s_waitcnt lgkmcnt(0)
	v_cvt_pk_bf16_f32 v0, v0, v1
	ds_read2_b32 v[2:3], v12 offset0:74 offset1:107
	s_waitcnt lgkmcnt(0)
	v_cvt_pk_bf16_f32 v1, v2, v3
	ds_read2_b32 v[2:3], v12 offset0:140 offset1:173
	s_waitcnt lgkmcnt(0)
	v_cvt_pk_bf16_f32 v2, v2, v3
	ds_read2_b32 v[4:5], v12 offset0:206 offset1:239
	s_waitcnt lgkmcnt(0)
	v_cvt_pk_bf16_f32 v3, v4, v5
	v_or_b32_e32 v4, 8, v6
	v_ashrrev_i32_e32 v5, 31, v4
	v_lshlrev_b64 v[4:5], 12, v[4:5]
	v_lshl_add_u64 v[4:5], v[8:9], 0, v[4:5]
	ds_read2_b32 v[10:11], v12 offset0:16 offset1:49
	global_store_dwordx4 v[4:5], v[0:3], off
	v_readlane_b32 s13, v253, 5
	v_readlane_b32 s14, v253, 6
	s_waitcnt lgkmcnt(0)
; #define LAS __attribute__((address_space(3)))
; #define LDS_WAIT() asm volatile("s_waitcnt lgkmcnt(0)" ::: "memory")
; __device__ __forceinline__ unsigned pk2(float lo, float hi) { return pg8::cvt_pk_bf16(lo, hi); }
; template <bool PERMUTE>
; __device__ __forceinline__ void p0_transpose_item(const float* W, int K, int N, bf16* WT, LAS float* scr, int item, int lane) {
;     const int nblk = N / 32, kb = item / nblk, nb = item % nblk, k0 = 64 * kb, n0 = 32 * nb;
;     float wv[32];
; #pragma unroll
;     for (int i = 0; i < 32; ++i) wv[i] = __builtin_nontemporal_load(W + (size_t)(k0 + 2 * i + (lane >> 5)) * N + n0 + (lane & 31));
; #pragma unroll
;     for (int i = 0; i < 32; ++i) scr[(2 * i + (lane >> 5)) * 33 + (lane & 31)] = wv[i];
;     LDS_WAIT(); asm volatile("" ::: "memory");
;     const int c = lane & 7;
; #pragma unroll
;     for (int j = 0; j < 4; ++j) { const int n = (lane >> 3) + 8 * j; const LAS float* s = scr + (8 * c) * 33 + n;
;         v4u o; o.x = pk2(s[0 * 33], s[1 * 33]); o.y = pk2(s[2 * 33], s[3 * 33]); o.z = pk2(s[4 * 33], s[5 * 33]); o.w = pk2(s[6 * 33], s[7 * 33]);
;         const int dr = PERMUTE ? win_dst_row(n0 + n) : (n0 + n);
;         if (PERMUTE && n0 < 4096) __builtin_nontemporal_store(o, (v4u*)(WT + (size_t)dr * K + k0 + 8 * c));
;         else *(v4u*)(WT + (size_t)dr * K + k0 + 8 * c) = o; }
;     LDS_WAIT(); asm volatile("" ::: "memory");
; }
; __global__ void __launch_bounds__(NWAVES * 64, 2) fwd_megakernel(Args a) {
;     ...
;                     __syncthreads();
	v_cvt_pk_bf16_f32 v0, v10, v11
	ds_read2_b32 v[2:3], v12 offset0:82 offset1:115
	s_waitcnt lgkmcnt(0)
	v_cvt_pk_bf16_f32 v1, v2, v3
	ds_read2_b32 v[2:3], v12 offset0:148 offset1:181
	s_waitcnt lgkmcnt(0)
	v_cvt_pk_bf16_f32 v2, v2, v3
	ds_read2_b32 v[4:5], v12 offset0:214 offset1:247
	s_waitcnt lgkmcnt(0)
	v_cvt_pk_bf16_f32 v3, v4, v5
	v_or_b32_e32 v4, 16, v6
	v_ashrrev_i32_e32 v5, 31, v4
	v_lshlrev_b64 v[4:5], 12, v[4:5]
	v_lshl_add_u64 v[4:5], v[8:9], 0, v[4:5]
	ds_read2_b32 v[10:11], v12 offset0:24 offset1:57
	global_store_dwordx4 v[4:5], v[0:3], off
	v_readlane_b32 s15, v253, 7
	v_readlane_b32 s16, v253, 8
	s_waitcnt lgkmcnt(0)
	v_cvt_pk_bf16_f32 v0, v10, v11
	ds_read2_b32 v[2:3], v12 offset0:90 offset1:123
	s_waitcnt lgkmcnt(0)
	v_cvt_pk_bf16_f32 v1, v2, v3
	ds_read2_b32 v[2:3], v12 offset0:156 offset1:189
	s_waitcnt lgkmcnt(0)
	v_cvt_pk_bf16_f32 v2, v2, v3
	ds_read2_b32 v[4:5], v12 offset0:222 offset1:255
	s_waitcnt lgkmcnt(0)
	v_cvt_pk_bf16_f32 v3, v4, v5
	v_or_b32_e32 v4, 24, v6
	v_ashrrev_i32_e32 v5, 31, v4
	v_lshlrev_b64 v[4:5], 12, v[4:5]
	v_lshl_add_u64 v[4:5], v[8:9], 0, v[4:5]
	global_store_dwordx4 v[4:5], v[0:3], off
	s_waitcnt lgkmcnt(0)
	v_readlane_b32 s17, v253, 9
	v_readlane_b32 s18, v253, 10
	v_readlane_b32 s19, v253, 11
	v_readlane_b32 s20, v253, 12
	v_readlane_b32 s21, v253, 13
	v_readlane_b32 s22, v253, 14
	v_readlane_b32 s23, v253, 15
	v_readlane_b32 s24, v253, 16
	v_readlane_b32 s25, v253, 17
	s_mov_b32 s2, s6
	s_mov_b32 s0, s10
	v_mul_u32_u24_e32 v175, 0x84, v136
	v_readlane_b32 s1, v253, 30
	s_ashr_i32 s3, s2, 31
	s_lshl_b64 s[2:3], s[2:3], 1
	v_add3_u32 v172, s1, v172, v175
	v_add_u32_e32 v175, 0x400, v172
	s_waitcnt vmcnt(30)
	ds_write2_b32 v172, v194, v195 offset1:66
	s_waitcnt vmcnt(28)
	ds_write2_b32 v172, v196, v197 offset0:132 offset1:198
	s_waitcnt vmcnt(26)
	ds_write2_b32 v175, v198, v199 offset0:8 offset1:74
	s_waitcnt vmcnt(24)
	ds_write2_b32 v175, v200, v201 offset0:140 offset1:206
	v_add_u32_e32 v175, 0x800, v172
	s_waitcnt vmcnt(22)
	ds_write2_b32 v175, v202, v203 offset0:16 offset1:82
	s_waitcnt vmcnt(20)
	ds_write2_b32 v175, v204, v205 offset0:148 offset1:214
	v_add_u32_e32 v175, 0xc00, v172
	s_waitcnt vmcnt(18)
	ds_write2_b32 v175, v206, v207 offset0:24 offset1:90
	s_waitcnt vmcnt(16)
	ds_write2_b32 v175, v208, v209 offset0:156 offset1:222
	v_add_u32_e32 v175, 0x1000, v172
	s_waitcnt vmcnt(14)
	ds_write2_b32 v175, v210, v211 offset0:32 offset1:98
	s_waitcnt vmcnt(12)
	ds_write2_b32 v175, v212, v213 offset0:164 offset1:230
	v_add_u32_e32 v175, 0x1400, v172
	s_waitcnt vmcnt(10)
	ds_write2_b32 v175, v214, v215 offset0:40 offset1:106
	s_waitcnt vmcnt(8)
	ds_write2_b32 v175, v216, v192 offset0:172 offset1:238
	v_add_u32_e32 v175, 0x1800, v172
	v_add_u32_e32 v172, 0x1c00, v172
	s_waitcnt vmcnt(6)
	ds_write2_b32 v175, v176, v177 offset0:48 offset1:114
	s_waitcnt vmcnt(4)
	ds_write2_b32 v175, v178, v179 offset0:180 offset1:246
	s_waitcnt vmcnt(2)
	ds_write2_b32 v172, v180, v181 offset0:56 offset1:122
	s_waitcnt vmcnt(0)
	ds_write2_b32 v172, v182, v174 offset0:188 offset1:254
	s_waitcnt lgkmcnt(0)
	v_mul_u32_u24_e32 v172, 0x84, v130
	v_lshlrev_b32_e32 v174, 2, v127
	v_add3_u32 v184, s1, v172, v174
	ds_read2_b32 v[174:175], v184 offset1:33
	s_waitcnt lgkmcnt(0)
	v_cvt_pk_bf16_f32 v174, v174, v175
	ds_read2_b32 v[176:177], v184 offset0:66 offset1:99
	s_waitcnt lgkmcnt(0)
	v_cvt_pk_bf16_f32 v175, v176, v177
	ds_read2_b32 v[176:177], v184 offset0:132 offset1:165
	s_waitcnt lgkmcnt(0)
	v_cvt_pk_bf16_f32 v176, v176, v177
	ds_read2_b32 v[178:179], v184 offset0:198 offset1:231
	v_readlane_b32 s4, v253, 48
	v_readlane_b32 s5, v253, 49
	s_add_u32 s2, s4, s2
	s_waitcnt lgkmcnt(0)
	v_cvt_pk_bf16_f32 v177, v178, v179
	v_or_b32_e32 v178, s0, v127
	s_addc_u32 s3, s5, s3
	v_mov_b32_e32 v99, v173
	v_ashrrev_i32_e32 v179, 31, v178
	v_lshl_add_u64 v[180:181], s[2:3], 0, v[98:99]
	v_lshlrev_b64 v[182:183], 12, v[178:179]
	ds_read2_b32 v[172:173], v184 offset0:8 offset1:41
	v_lshl_add_u64 v[182:183], v[180:181], 0, v[182:183]
	global_store_dwordx4 v[182:183], v[174:177], off
	s_waitcnt lgkmcnt(0)
	v_cvt_pk_bf16_f32 v172, v172, v173
	ds_read2_b32 v[174:175], v184 offset0:74 offset1:107
	s_waitcnt lgkmcnt(0)
	v_cvt_pk_bf16_f32 v173, v174, v175
	ds_read2_b32 v[174:175], v184 offset0:140 offset1:173
	s_waitcnt lgkmcnt(0)
	v_cvt_pk_bf16_f32 v174, v174, v175
	ds_read2_b32 v[176:177], v184 offset0:206 offset1:239
	s_waitcnt lgkmcnt(0)
	v_cvt_pk_bf16_f32 v175, v176, v177
	v_or_b32_e32 v176, 8, v178
	v_ashrrev_i32_e32 v177, 31, v176
	v_lshlrev_b64 v[176:177], 12, v[176:177]
	v_lshl_add_u64 v[176:177], v[180:181], 0, v[176:177]
	ds_read2_b32 v[182:183], v184 offset0:16 offset1:49
	global_store_dwordx4 v[176:177], v[172:175], off
	v_readlane_b32 s13, v253, 5
	v_readlane_b32 s14, v253, 6
	s_waitcnt lgkmcnt(0)
	v_cvt_pk_bf16_f32 v172, v182, v183
	ds_read2_b32 v[174:175], v184 offset0:82 offset1:115
	s_waitcnt lgkmcnt(0)
	v_cvt_pk_bf16_f32 v173, v174, v175
	ds_read2_b32 v[174:175], v184 offset0:148 offset1:181
	s_waitcnt lgkmcnt(0)
	v_cvt_pk_bf16_f32 v174, v174, v175
	ds_read2_b32 v[176:177], v184 offset0:214 offset1:247
	s_waitcnt lgkmcnt(0)
	v_cvt_pk_bf16_f32 v175, v176, v177
	v_or_b32_e32 v176, 16, v178
	v_ashrrev_i32_e32 v177, 31, v176
	v_lshlrev_b64 v[176:177], 12, v[176:177]
	v_lshl_add_u64 v[176:177], v[180:181], 0, v[176:177]
	ds_read2_b32 v[182:183], v184 offset0:24 offset1:57
	global_store_dwordx4 v[176:177], v[172:175], off
	v_readlane_b32 s15, v253, 7
	v_readlane_b32 s16, v253, 8
	s_waitcnt lgkmcnt(0)
	v_cvt_pk_bf16_f32 v172, v182, v183
	ds_read2_b32 v[174:175], v184 offset0:90 offset1:123
	s_waitcnt lgkmcnt(0)
	v_cvt_pk_bf16_f32 v173, v174, v175
	ds_read2_b32 v[174:175], v184 offset0:156 offset1:189
	s_waitcnt lgkmcnt(0)
	v_cvt_pk_bf16_f32 v174, v174, v175
	ds_read2_b32 v[176:177], v184 offset0:222 offset1:255
	s_waitcnt lgkmcnt(0)
	v_cvt_pk_bf16_f32 v175, v176, v177
	v_or_b32_e32 v176, 24, v178
	v_ashrrev_i32_e32 v177, 31, v176
	v_lshlrev_b64 v[176:177], 12, v[176:177]
	v_lshl_add_u64 v[176:177], v[180:181], 0, v[176:177]
	global_store_dwordx4 v[176:177], v[172:175], off
	s_waitcnt lgkmcnt(0)
	v_readlane_b32 s17, v253, 9
	v_readlane_b32 s18, v253, 10
	v_readlane_b32 s19, v253, 11
	v_readlane_b32 s20, v253, 12
	v_readlane_b32 s21, v253, 13
	v_readlane_b32 s22, v253, 14
	v_readlane_b32 s23, v253, 15
	v_readlane_b32 s24, v253, 16
	v_readlane_b32 s25, v253, 17
	s_barrier
	s_branch .LBB0_303
